# grid barrier: L1 invalidate issued right after the arrival atomic instead of after release
# speedup vs baseline: 1.0070x; 1.0070x over previous
.LBB0_272:
	s_lshl_b32 s20, s28, 6
	s_add_i32 s2, s20, 0x500
	s_mov_b32 s3, 0
	s_lshl_b64 s[0:1], s[2:3], 2
	s_add_u32 s0, s34, s0
	s_addc_u32 s1, s35, s1
	v_mov_b32_e32 v1, 1
	v_mov_b64_e32 v[4:5], s[0:1]
	flat_atomic_add v1, v[4:5], v1 sc0
	buffer_inv sc1
	v_cvt_f32_u32_e32 v3, v2
	v_sub_u32_e32 v4, 0, v2
	v_rcp_iflag_f32_e32 v3, v3
	s_nop 0
	v_mul_f32_e32 v3, 0x4f7ffffe, v3
	v_cvt_u32_f32_e32 v3, v3
	v_mul_lo_u32 v4, v4, v3
	v_mul_hi_u32 v4, v3, v4
	v_add_u32_e32 v3, v3, v4
	s_waitcnt vmcnt(0) lgkmcnt(0)
	v_mul_hi_u32 v3, v1, v3
	v_mul_lo_u32 v5, v3, v2
	v_add_u32_e32 v4, 1, v1
	v_sub_u32_e32 v1, v1, v5
	v_add_u32_e32 v6, 1, v3
	v_cmp_ge_u32_e32 vcc, v1, v2
	v_sub_u32_e32 v5, v1, v2
	s_nop 0
	v_cndmask_b32_e32 v3, v3, v6, vcc
	v_cndmask_b32_e32 v1, v1, v5, vcc
	v_add_u32_e32 v5, 1, v3
	v_cmp_ge_u32_e32 vcc, v1, v2
	s_nop 1
	v_cndmask_b32_e32 v1, v3, v5, vcc
	v_mad_u64_u32 v[2:3], s[0:1], v2, v1, v[2:3]
	v_cmp_ne_u32_e32 vcc, v4, v2
	s_and_saveexec_b64 s[0:1], vcc
	s_xor_b64 s[0:1], exec, s[0:1]
	s_cbranch_execz .LBB0_285
	s_add_i32 s2, s20, 0x900
	s_lshl_b64 s[2:3], s[2:3], 2
	s_add_u32 s4, s34, s2
	s_addc_u32 s5, s35, s3
	v_mov_b64_e32 v[2:3], s[4:5]
	flat_load_dword v0, v[2:3] sc1
	s_waitcnt vmcnt(0) lgkmcnt(0)
	v_cmp_eq_u32_e32 vcc, v0, v1
	s_and_saveexec_b64 s[2:3], vcc
	s_cbranch_execz .LBB0_284
	s_mov_b32 s21, 1
	s_mov_b64 s[6:7], 0
	s_branch .LBB0_276

.LBB0_284:
	s_or_b64 exec, exec, s[2:3]
	s_waitcnt vmcnt(0) lgkmcnt(0)
	s_waitcnt vmcnt(0)

.LBB0_300:
	s_or_b64 exec, exec, s[0:1]
	s_add_i32 s0, s20, 0x900
	s_mov_b32 s1, 0
	s_lshl_b64 s[0:1], s[0:1], 2
	s_add_u32 s0, s34, s0
	s_addc_u32 s1, s35, s1
	v_mov_b32_e32 v2, 1
	v_mov_b64_e32 v[0:1], s[0:1]
	s_waitcnt vmcnt(0) lgkmcnt(0)
	flat_atomic_add v[0:1], v2
	s_waitcnt vmcnt(0)

.LBB0_303:
	s_or_b64 exec, exec, s[0:1]
	s_add_i32 s38, s20, 0x900
	s_lshl_b64 s[0:1], s[38:39], 2
	s_add_u32 s0, s34, s0
	s_addc_u32 s1, s35, s1
	v_mov_b64_e32 v[0:1], s[0:1]
	s_waitcnt vmcnt(0) lgkmcnt(0)
	flat_atomic_add v[0:1], v249
	s_waitcnt vmcnt(0)

.LBB0_401:
	s_lshl_b32 s20, s28, 6
	s_add_i32 s38, s20, 0x500
	s_lshl_b64 s[0:1], s[38:39], 2
	s_add_u32 s0, s54, s0
	s_addc_u32 s1, s55, s1
	v_mov_b64_e32 v[4:5], s[0:1]
	flat_atomic_add v3, v[4:5], v249 sc0
	buffer_inv sc1
	v_cvt_f32_u32_e32 v1, v2
	v_sub_u32_e32 v4, 0, v2
	v_rcp_iflag_f32_e32 v1, v1
	s_nop 0
	v_mul_f32_e32 v1, 0x4f7ffffe, v1
	v_cvt_u32_f32_e32 v1, v1
	v_mul_lo_u32 v4, v4, v1
	v_mul_hi_u32 v4, v1, v4
	v_add_u32_e32 v1, v1, v4
	s_waitcnt vmcnt(0) lgkmcnt(0)
	v_mul_hi_u32 v1, v3, v1
	v_mul_lo_u32 v4, v1, v2
	v_sub_u32_e32 v4, v3, v4
	v_cmp_ge_u32_e32 vcc, v4, v2
	v_add_u32_e32 v5, 1, v1
	s_nop 0
	v_cndmask_b32_e32 v1, v1, v5, vcc
	v_sub_u32_e32 v5, v4, v2
	v_cndmask_b32_e32 v4, v4, v5, vcc
	v_cmp_ge_u32_e32 vcc, v4, v2
	v_add_u32_e32 v4, 1, v1
	s_nop 0
	v_cndmask_b32_e32 v1, v1, v4, vcc
	v_add_u32_e32 v4, 1, v3
	v_mad_u64_u32 v[2:3], s[0:1], v2, v1, v[2:3]
	v_cmp_ne_u32_e32 vcc, v4, v2
	s_and_saveexec_b64 s[0:1], vcc
	s_xor_b64 s[0:1], exec, s[0:1]
	s_cbranch_execz .LBB0_414
	s_add_i32 s38, s20, 0x900
	s_lshl_b64 s[2:3], s[38:39], 2
	s_add_u32 s4, s54, s2
	s_addc_u32 s5, s55, s3
	v_mov_b64_e32 v[2:3], s[4:5]
	flat_load_dword v0, v[2:3] sc1
	s_waitcnt vmcnt(0) lgkmcnt(0)
	v_cmp_eq_u32_e32 vcc, v0, v1
	s_and_saveexec_b64 s[2:3], vcc
	s_cbranch_execz .LBB0_413
	s_mov_b32 s21, 1
	s_mov_b64 s[6:7], 0
	s_branch .LBB0_405

.LBB0_429:
	s_or_b64 exec, exec, s[0:1]
	s_add_i32 s38, s20, 0x900
	s_lshl_b64 s[0:1], s[38:39], 2
	s_add_u32 s0, s54, s0
	s_addc_u32 s1, s55, s1
	v_mov_b64_e32 v[0:1], s[0:1]
	s_waitcnt vmcnt(0) lgkmcnt(0)
	flat_atomic_add v[0:1], v249
	s_waitcnt vmcnt(0)

.LBB0_628:
	s_lshl_b32 s20, s28, 6
	s_add_i32 s38, s20, 0x500
	s_lshl_b64 s[0:1], s[38:39], 2
	s_add_u32 s0, s34, s0
	s_addc_u32 s1, s35, s1
	v_mov_b64_e32 v[4:5], s[0:1]
	flat_atomic_add v3, v[4:5], v249 sc0
	buffer_inv sc1
	v_cvt_f32_u32_e32 v1, v2
	v_sub_u32_e32 v4, 0, v2
	v_rcp_iflag_f32_e32 v1, v1
	s_nop 0
	v_mul_f32_e32 v1, 0x4f7ffffe, v1
	v_cvt_u32_f32_e32 v1, v1
	v_mul_lo_u32 v4, v4, v1
	v_mul_hi_u32 v4, v1, v4
	v_add_u32_e32 v1, v1, v4
	s_waitcnt vmcnt(0) lgkmcnt(0)
	v_mul_hi_u32 v1, v3, v1
	v_mul_lo_u32 v4, v1, v2
	v_sub_u32_e32 v4, v3, v4
	v_cmp_ge_u32_e32 vcc, v4, v2
	v_add_u32_e32 v5, 1, v1
	s_nop 0
	v_cndmask_b32_e32 v1, v1, v5, vcc
	v_sub_u32_e32 v5, v4, v2
	v_cndmask_b32_e32 v4, v4, v5, vcc
	v_cmp_ge_u32_e32 vcc, v4, v2
	v_add_u32_e32 v4, 1, v1
	s_nop 0
	v_cndmask_b32_e32 v1, v1, v4, vcc
	v_add_u32_e32 v4, 1, v3
	v_mad_u64_u32 v[2:3], s[0:1], v2, v1, v[2:3]
	v_cmp_ne_u32_e32 vcc, v4, v2
	s_and_saveexec_b64 s[0:1], vcc
	s_xor_b64 s[0:1], exec, s[0:1]
	s_cbranch_execz .LBB0_641
	s_add_i32 s38, s20, 0x900
	s_lshl_b64 s[2:3], s[38:39], 2
	s_add_u32 s4, s34, s2
	s_addc_u32 s5, s35, s3
	v_mov_b64_e32 v[2:3], s[4:5]
	flat_load_dword v0, v[2:3] sc1
	s_waitcnt vmcnt(0) lgkmcnt(0)
	v_cmp_eq_u32_e32 vcc, v0, v1
	s_and_saveexec_b64 s[2:3], vcc
	s_cbranch_execz .LBB0_640
	s_mov_b32 s21, 1
	s_mov_b64 s[6:7], 0
	s_branch .LBB0_632

.LBB0_1713:
	s_lshl_b32 s0, s0, 6
	s_add_i32 s38, s0, 0x500
	s_lshl_b64 s[2:3], s[38:39], 2
	s_add_u32 s2, s56, s2
	s_addc_u32 s3, s57, s3
	v_mov_b64_e32 v[4:5], s[2:3]
	flat_atomic_add v3, v[4:5], v249 sc0
	buffer_inv sc1
	v_cvt_f32_u32_e32 v1, v2
	v_sub_u32_e32 v4, 0, v2
	v_rcp_iflag_f32_e32 v1, v1
	s_nop 0
	v_mul_f32_e32 v1, 0x4f7ffffe, v1
	v_cvt_u32_f32_e32 v1, v1
	v_mul_lo_u32 v4, v4, v1
	v_mul_hi_u32 v4, v1, v4
	v_add_u32_e32 v1, v1, v4
	s_waitcnt vmcnt(0) lgkmcnt(0)
	v_mul_hi_u32 v1, v3, v1
	v_mul_lo_u32 v4, v1, v2
	v_sub_u32_e32 v4, v3, v4
	v_cmp_ge_u32_e32 vcc, v4, v2
	v_add_u32_e32 v5, 1, v1
	s_nop 0
	v_cndmask_b32_e32 v1, v1, v5, vcc
	v_sub_u32_e32 v5, v4, v2
	v_cndmask_b32_e32 v4, v4, v5, vcc
	v_cmp_ge_u32_e32 vcc, v4, v2
	v_add_u32_e32 v4, 1, v1
	s_nop 0
	v_cndmask_b32_e32 v1, v1, v4, vcc
	v_add_u32_e32 v4, 1, v3
	v_mad_u64_u32 v[2:3], s[2:3], v2, v1, v[2:3]
	v_cmp_ne_u32_e32 vcc, v4, v2
	s_and_saveexec_b64 s[2:3], vcc
	s_xor_b64 s[2:3], exec, s[2:3]
	s_cbranch_execz .LBB0_1726
	s_add_i32 s38, s0, 0x900
	s_lshl_b64 s[4:5], s[38:39], 2
	s_add_u32 s6, s56, s4
	s_addc_u32 s7, s57, s5
	v_mov_b64_e32 v[2:3], s[6:7]
	flat_load_dword v0, v[2:3] sc1
	s_waitcnt vmcnt(0) lgkmcnt(0)
	v_cmp_eq_u32_e32 vcc, v0, v1
	s_and_saveexec_b64 s[4:5], vcc
	s_cbranch_execz .LBB0_1725
	s_mov_b32 s1, 1
	s_mov_b64 s[8:9], 0
	s_branch .LBB0_1717

.LBB0_1725:
	s_or_b64 exec, exec, s[4:5]
	s_waitcnt vmcnt(0) lgkmcnt(0)
	s_waitcnt vmcnt(0)

.LBB0_1741:
	s_or_b64 exec, exec, s[2:3]
	s_add_i32 s38, s0, 0x900
	s_lshl_b64 s[0:1], s[38:39], 2
	s_add_u32 s0, s56, s0
	s_addc_u32 s1, s57, s1
	v_mov_b64_e32 v[0:1], s[0:1]
	s_waitcnt vmcnt(0) lgkmcnt(0)
	flat_atomic_add v[0:1], v249
	s_waitcnt vmcnt(0)

.LBB0_1851:
	s_lshl_b32 s0, s0, 6
	s_add_i32 s38, s0, 0x500
	s_lshl_b64 s[2:3], s[38:39], 2
	s_add_u32 s2, s62, s2
	s_addc_u32 s3, s63, s3
	v_mov_b64_e32 v[4:5], s[2:3]
	flat_atomic_add v3, v[4:5], v249 sc0
	buffer_inv sc1
	v_cvt_f32_u32_e32 v1, v2
	v_sub_u32_e32 v4, 0, v2
	v_rcp_iflag_f32_e32 v1, v1
	s_nop 0
	v_mul_f32_e32 v1, 0x4f7ffffe, v1
	v_cvt_u32_f32_e32 v1, v1
	v_mul_lo_u32 v4, v4, v1
	v_mul_hi_u32 v4, v1, v4
	v_add_u32_e32 v1, v1, v4
	s_waitcnt vmcnt(0) lgkmcnt(0)
	v_mul_hi_u32 v1, v3, v1
	v_mul_lo_u32 v4, v1, v2
	v_sub_u32_e32 v4, v3, v4
	v_cmp_ge_u32_e32 vcc, v4, v2
	v_add_u32_e32 v5, 1, v1
	s_nop 0
	v_cndmask_b32_e32 v1, v1, v5, vcc
	v_sub_u32_e32 v5, v4, v2
	v_cndmask_b32_e32 v4, v4, v5, vcc
	v_cmp_ge_u32_e32 vcc, v4, v2
	v_add_u32_e32 v4, 1, v1
	s_nop 0
	v_cndmask_b32_e32 v1, v1, v4, vcc
	v_add_u32_e32 v4, 1, v3
	v_mad_u64_u32 v[2:3], s[2:3], v2, v1, v[2:3]
	v_cmp_ne_u32_e32 vcc, v4, v2
	s_and_saveexec_b64 s[2:3], vcc
	s_xor_b64 s[2:3], exec, s[2:3]
	s_cbranch_execz .LBB0_1864
	s_add_i32 s38, s0, 0x900
	s_lshl_b64 s[4:5], s[38:39], 2
	s_add_u32 s6, s62, s4
	s_addc_u32 s7, s63, s5
	v_mov_b64_e32 v[2:3], s[6:7]
	flat_load_dword v0, v[2:3] sc1
	s_waitcnt vmcnt(0) lgkmcnt(0)
	v_cmp_eq_u32_e32 vcc, v0, v1
	s_and_saveexec_b64 s[4:5], vcc
	s_cbranch_execz .LBB0_1863
	s_mov_b32 s1, 1
	s_mov_b64 s[8:9], 0
	s_branch .LBB0_1855

.LBB0_1879:
	s_or_b64 exec, exec, s[2:3]
	s_add_i32 s38, s0, 0x900
	s_lshl_b64 s[0:1], s[38:39], 2
	s_add_u32 s0, s62, s0
	s_addc_u32 s1, s63, s1
	v_mov_b64_e32 v[0:1], s[0:1]
	s_waitcnt vmcnt(0) lgkmcnt(0)
	flat_atomic_add v[0:1], v249
	s_waitcnt vmcnt(0)

.LBB0_1968:
	s_lshl_b32 s0, s0, 6
	s_add_i32 s38, s0, 0x500
	s_lshl_b64 s[2:3], s[38:39], 2
	s_add_u32 s2, s60, s2
	s_addc_u32 s3, s61, s3
	v_mov_b64_e32 v[4:5], s[2:3]
	flat_atomic_add v3, v[4:5], v249 sc0
	buffer_inv sc1
	v_cvt_f32_u32_e32 v1, v2
	v_sub_u32_e32 v4, 0, v2
	v_rcp_iflag_f32_e32 v1, v1
	s_nop 0
	v_mul_f32_e32 v1, 0x4f7ffffe, v1
	v_cvt_u32_f32_e32 v1, v1
	v_mul_lo_u32 v4, v4, v1
	v_mul_hi_u32 v4, v1, v4
	v_add_u32_e32 v1, v1, v4
	s_waitcnt vmcnt(0) lgkmcnt(0)
	v_mul_hi_u32 v1, v3, v1
	v_mul_lo_u32 v4, v1, v2
	v_sub_u32_e32 v4, v3, v4
	v_cmp_ge_u32_e32 vcc, v4, v2
	v_add_u32_e32 v5, 1, v1
	s_nop 0
	v_cndmask_b32_e32 v1, v1, v5, vcc
	v_sub_u32_e32 v5, v4, v2
	v_cndmask_b32_e32 v4, v4, v5, vcc
	v_cmp_ge_u32_e32 vcc, v4, v2
	v_add_u32_e32 v4, 1, v1
	s_nop 0
	v_cndmask_b32_e32 v1, v1, v4, vcc
	v_add_u32_e32 v4, 1, v3
	v_mad_u64_u32 v[2:3], s[2:3], v2, v1, v[2:3]
	v_cmp_ne_u32_e32 vcc, v4, v2
	s_and_saveexec_b64 s[2:3], vcc
	s_xor_b64 s[2:3], exec, s[2:3]
	s_cbranch_execz .LBB0_1981
	s_add_i32 s38, s0, 0x900
	s_lshl_b64 s[4:5], s[38:39], 2
	s_add_u32 s6, s60, s4
	s_addc_u32 s7, s61, s5
	v_mov_b64_e32 v[2:3], s[6:7]
	flat_load_dword v0, v[2:3] sc1
	s_waitcnt vmcnt(0) lgkmcnt(0)
	v_cmp_eq_u32_e32 vcc, v0, v1
	s_and_saveexec_b64 s[4:5], vcc
	s_cbranch_execz .LBB0_1980
	s_mov_b32 s1, 1
	s_mov_b64 s[8:9], 0
	s_branch .LBB0_1972

.LBB0_1996:
	s_or_b64 exec, exec, s[2:3]
	s_add_i32 s38, s0, 0x900
	s_lshl_b64 s[0:1], s[38:39], 2
	s_add_u32 s0, s60, s0
	s_addc_u32 s1, s61, s1
	v_mov_b64_e32 v[0:1], s[0:1]
	s_waitcnt vmcnt(0) lgkmcnt(0)
	flat_atomic_add v[0:1], v5
	s_waitcnt vmcnt(0)
	v_mov_b32_e32 v249, v5
